# scan: hand-written compute loop (per-lane LDS selects, hi-half op_sel, pair-ahead LDS prefetch) + fused DPP adds in loader
# speedup vs baseline: 1.0231x; 1.0231x over previous
; __device__ __forceinline__ void lds_barrier() { asm volatile("s_waitcnt lgkmcnt(0)\n\ts_barrier" ::: "memory"); }
; __device__ void rwscan_item(const Params& p, int l, int item, unsigned char* ldsraw) {
;     ...
;     typedef float f32x2 __attribute__((ext_vector_type(2)));
;     f32x2 sa = {0.f, 0.f}, sb = {0.f, 0.f};
;     const int row = q4 * 16 + wave * 4 + rsel;
;     const bool bit0 = (lane & 1) != 0, bit1 = (lane & 2) != 0, isy1 = (cg & 3) == 2;
;     u16* yl = (u16*)(p.ws + WS_ABUF) + (tokb + 2 * (cg >> 2) + (cg & 1)) * D + 384 + h * 64 + row;
;     lds_barrier();
.LBB0_312:
	v_readlane_b32 s6, v160, 28
	s_andn2_b64 vcc, exec, s[0:1]
	v_readlane_b32 s7, v160, 29
	s_cbranch_vccnz .LBB0_400
	s_and_b64 vcc, exec, s[4:5]
	s_cbranch_vccnz .LBB0_400
	v_readlane_b32 s0, v162, 25
	v_mov_b32_e32 v52, v68
	s_add_u32 s18, s0, s2
	v_readlane_b32 s0, v162, 26
	s_addc_u32 s19, s0, s3
	v_ashrrev_i32_e32 v23, 6, v52
	v_and_b32_e32 v20, 15, v52
	v_bfe_u32 v7, v52, 4, 2
	v_cmp_gt_i32_e32 vcc, 4, v23
	s_and_saveexec_b64 s[0:1], vcc
	s_xor_b64 s[0:1], exec, s[0:1]
	s_movk_i32 s29, 0x300
	s_movk_i32 s30, 0x940
	s_mov_b64 s[16:17], 0x1980300
	s_mov_b64 s[34:35], 0x4000
	s_cbranch_execz .LBB0_364
	v_lshlrev_b32_e32 v35, 2, v23
	v_readlane_b32 s4, v162, 22
	v_and_b32_e32 v3, 2, v52
	v_cmp_ne_u32_e64 s[6:7], 0, v3
	v_add_u32_e32 v0, s4, v35
	v_cmp_eq_u32_e64 s[4:5], 0, v3
	v_and_b32_e32 v3, 3, v52
	v_lshrrev_b32_e32 v8, 2, v20
	v_readlane_b32 s10, v162, 18
	v_or_b32_e32 v2, v0, v7
	v_and_b32_e32 v0, 1, v52
	v_cmp_eq_u32_e64 s[8:9], 2, v3
	v_lshlrev_b32_e32 v3, 1, v8
	v_readlane_b32 s11, v162, 19
	v_or3_b32 v4, v3, v0, s10
	v_readlane_b32 s12, v161, 44
	v_mov_b32_e32 v5, s11
	v_lshlrev_b64 v[4:5], 11, v[4:5]
	v_readlane_b32 s14, v161, 46
	v_readlane_b32 s15, v161, 47
	v_readlane_b32 s10, v162, 20
	v_readlane_b32 s11, v162, 21
	v_lshl_add_u64 v[4:5], s[14:15], 0, v[4:5]
	v_ashrrev_i32_e32 v3, 31, v2
	v_lshl_add_u64 v[4:5], s[10:11], 1, v[4:5]
	v_mov_b32_e32 v56, 0x910
	v_mov_b32_e32 v10, 0x908
	v_mov_b32_e32 v57, 0x918
	v_mov_b32_e32 v11, 0x920
	v_cndmask_b32_e64 v56, v56, v10, s[8:9]
	v_cndmask_b32_e64 v57, v57, v11, s[8:9]
	v_lshlrev_b32_e32 v58, 4, v23
	v_lshl_add_u32 v58, v7, 2, v58
	v_add_u32_e32 v58, 0x2400, v58
	v_and_b32_e32 v10, 1, v52
	v_mul_u32_u24_e32 v10, 0x2700, v10
	v_bfe_u32 v11, v52, 1, 2
	v_mul_u32_u24_e32 v11, 0x940, v11
	v_add_u32_e32 v10, 0xa20, v10
	v_add_u32_e32 v10, v10, v11
	v_mov_b32_e32 v12, 0
	v_mov_b32_e32 v13, 0
	ds_write_b64 v10, v[12:13]
	s_waitcnt lgkmcnt(0)
	s_barrier
	v_readlane_b32 s13, v161, 45
	v_lshl_add_u64 v[2:3], v[2:3], 1, v[4:5]
	v_mov_b32_e32 v30, 0
	s_mov_b32 s24, 0
	v_cmp_eq_u32_e32 vcc, 0, v0
	v_lshl_add_u64 v[24:25], v[2:3], 0, s[16:17]
	v_lshlrev_b32_e32 v47, 4, v20
	v_cmp_eq_u32_e64 s[10:11], 3, v8
	v_cmp_eq_u32_e64 s[12:13], 2, v8
	v_cmp_eq_u32_e64 s[14:15], 1, v8
	v_cmp_gt_u32_e64 s[16:17], 4, v20
	v_mov_b32_e32 v31, v30
	v_mov_b32_e32 v32, v30
	v_mov_b32_e32 v33, v30
	s_waitcnt vmcnt(0)
	s_branch .LBB0_360

; __device__ void rwscan_item(const Params& p, int l, int item, unsigned char* ldsraw) {
;     ...
;     for (int ch = 0; ch < nch; ++ch) {
;       const float* cb = lp + (ch & 1) * CHF;
;       float yv[4];
; #pragma unroll
;       for (int j = 0; j < 4; ++j) {
;         const f32x2* pb = (const f32x2*)(cb + j * PRF + cg * 4);
;     ...
;         LDV(0, A1a, A1b) LDV(1, A2a, A2b) LDV(2, A3a, A3b) LDV(3, A4a, A4b)
;         LDV(4, U0a, U0b) LDV(5, U1a, U1b) LDV(6, U2a, U2b) LDV(7, U3a, U3b) LDV(8, U4a, U4b)
;     ...
;         const float4 ca = *(const float4*)(cb + j * PRF + 576), cc = *(const float4*)(cb + j * PRF + 580);
;         const float v1 = cb[4 * PRF + (2 * j) * 16 + wave * 4 + rsel];
;         const float v2 = cb[4 * PRF + (2 * j + 1) * 16 + wave * 4 + rsel];
;         f32x2 t1 = sa * A1a + sb * A1b, t2 = sa * A2a + sb * A2b, t3 = sa * A3a + sb * A3b, t4 = sa * A4a + sb * A4b;
;         const float p1 = t1.x + t1.y, p2 = t2.x + t2.y, p3 = t3.x + t3.y, p4 = t4.x + t4.y;
;         const float u12 = (bit0 ? p2 : p1) + dppx<0xB1>(bit0 ? p1 : p2);
;         const float u34 = (bit0 ? p4 : p3) + dppx<0xB1>(bit0 ? p3 : p4);
;         float wq = (bit1 ? u34 : u12) + dppx<0x4E>(bit1 ? u12 : u34);
;         wq += dppx<0x124>(wq);
;         wq += dppx<0x128>(wq);
;         const float d1 = -dppx<0x00>(wq);
;         const float d2 = -(dppx<0x55>(wq) + d1 * ca.x + v1 * ca.y);
;         const float e1 = isy1 ? ca.z : cc.x, e2 = isy1 ? ca.w : cc.y, e3 = isy1 ? 0.f : cc.z, e4 = isy1 ? 0.f : cc.w;
;         yv[j] = wq + d1 * e1 + v1 * e2 + d2 * e3 + v2 * e4;
;         sa = sa * U0a + d1 * U1a + v1 * U2a + d2 * U3a + v2 * U4a;
;         sb = sb * U0b + d1 * U1b + v1 * U2b + d2 * U3b + v2 * U4b;
.LBB0_360:
	s_bitcmp1_b32 s24, 0
	s_cselect_b32 s25, 0x2700, 0
	s_add_i32 s25, s25, 0x100
	v_add_u32_e32 v46, s25, v47
	v_add_u32_e32 v53, s25, v58
	v_add_u32_e32 v54, s25, v56
	v_add_u32_e32 v55, s25, v57
	v_mov_b32_e32 v59, s25
	ds_read_b128 v[164:167], v46 offset:0
	ds_read_b128 v[168:171], v46 offset:256
	ds_read_b128 v[172:175], v46 offset:512
	ds_read_b128 v[176:179], v46 offset:768
	ds_read_b128 v[180:183], v46 offset:1024
	ds_read_b128 v[184:187], v46 offset:1280
	ds_read_b128 v[188:191], v46 offset:1536
	ds_read_b128 v[192:195], v46 offset:1792
	ds_read_b128 v[196:199], v46 offset:2048
	ds_read_b32 v201, v53 offset:256
	ds_read_b32 v203, v53 offset:320
	ds_read_b64 v[204:205], v59 offset:2304
	ds_read_b64 v[206:207], v54 offset:0
	ds_read_b64 v[208:209], v55 offset:0
	s_waitcnt lgkmcnt(10)
	v_pk_mul_f32 v[2:3], v[32:33], v[166:167]
	v_pk_mul_f32 v[4:5], v[32:33], v[170:171]
	v_pk_mul_f32 v[8:9], v[32:33], v[174:175]
	v_pk_mul_f32 v[10:11], v[32:33], v[178:179]
	v_pk_fma_f32 v[2:3], v[30:31], v[164:165], v[2:3]
	v_pk_fma_f32 v[4:5], v[30:31], v[168:169], v[4:5]
	v_pk_fma_f32 v[8:9], v[30:31], v[172:173], v[8:9]
	v_pk_fma_f32 v[10:11], v[30:31], v[176:177], v[10:11]
	v_add_f32_e32 v12, v2, v3
	v_add_f32_e32 v13, v4, v5
	v_add_f32_e32 v14, v8, v9
	v_add_f32_e32 v15, v10, v11
	v_cndmask_b32_e32 v17, v12, v13, vcc
	v_cndmask_b32_e32 v19, v14, v15, vcc
	v_cndmask_b32_e32 v16, v13, v12, vcc
	v_cndmask_b32_e32 v18, v15, v14, vcc
	v_add_f32_dpp v17, v17, v16 quad_perm:[1,0,3,2] row_mask:0xf bank_mask:0xf bound_ctrl:1
	v_add_f32_dpp v19, v19, v18 quad_perm:[1,0,3,2] row_mask:0xf bank_mask:0xf bound_ctrl:1
	v_cndmask_b32_e64 v16, v19, v17, s[4:5]
	v_cndmask_b32_e64 v18, v17, v19, s[4:5]
	s_waitcnt lgkmcnt(5)
	ds_read_b128 v[210:213], v46 offset:2368
	ds_read_b128 v[214:217], v46 offset:2624
	v_add_f32_dpp v18, v18, v16 quad_perm:[2,3,0,1] row_mask:0xf bank_mask:0xf bound_ctrl:1
	ds_read_b128 v[218:221], v46 offset:2880
	ds_read_b128 v[222:225], v46 offset:3136
	v_add_f32_dpp v18, v18, v18 row_ror:4 row_mask:0xf bank_mask:0xf bound_ctrl:1
	ds_read_b128 v[226:229], v46 offset:3392
	ds_read_b128 v[230:233], v46 offset:3648
	v_add_f32_dpp v20, v18, v18 row_ror:8 row_mask:0xf bank_mask:0xf bound_ctrl:1
	ds_read_b128 v[234:237], v46 offset:3904
	ds_read_b128 v[238:241], v46 offset:4160
	s_waitcnt lgkmcnt(8)
	v_mov_b32_dpp v200, v20 quad_perm:[0,0,0,0] row_mask:0xf bank_mask:0xf bound_ctrl:1
	v_pk_mul_f32 v[22:23], v[204:205], v[200:201]
	v_pk_mul_f32 v[36:37], v[184:185], v[200:201] op_sel_hi:[1,0] neg_lo:[0,1] neg_hi:[0,1]
	ds_read_b128 v[242:245], v46 offset:4416
	v_pk_mul_f32 v[38:39], v[186:187], v[200:201] op_sel_hi:[1,0] neg_lo:[0,1] neg_hi:[0,1]
	v_sub_f32_dpp v21, v20, v22 quad_perm:[1,1,1,1] row_mask:0xf bank_mask:0xf bound_ctrl:1
	v_fma_f32 v26, -v206, v200, v20
	v_pk_fma_f32 v[36:37], v[30:31], v[180:181], v[36:37]
	v_add_f32_e32 v202, v23, v21
	ds_read_b32 v247, v53 offset:384
	v_pk_fma_f32 v[38:39], v[32:33], v[182:183], v[38:39]
	v_fmac_f32_e32 v26, v201, v207
	v_pk_fma_f32 v[36:37], v[188:189], v[200:201], v[36:37] op_sel:[0,1,0] op_sel_hi:[1,1,1]
	v_pk_fma_f32 v[38:39], v[190:191], v[200:201], v[38:39] op_sel:[0,1,0] op_sel_hi:[1,1,1]
	ds_read_b32 v249, v53 offset:448
	v_fma_f32 v26, -v202, v208, v26
	v_pk_fma_f32 v[36:37], v[192:193], v[202:203], v[36:37] op_sel_hi:[1,0,1] neg_lo:[0,1,0] neg_hi:[0,1,0]
	v_pk_fma_f32 v[38:39], v[194:195], v[202:203], v[38:39] op_sel_hi:[1,0,1] neg_lo:[0,1,0] neg_hi:[0,1,0]
	ds_read_b64 v[250:251], v59 offset:4672
	v_fmac_f32_e32 v26, v203, v209
	v_pk_fma_f32 v[30:31], v[196:197], v[202:203], v[36:37] op_sel:[0,1,0] op_sel_hi:[1,1,1]
	v_pk_fma_f32 v[32:33], v[198:199], v[202:203], v[38:39] op_sel:[0,1,0] op_sel_hi:[1,1,1]
	ds_read_b64 v[252:253], v54 offset:2368
	ds_read_b64 v[254:255], v55 offset:2368
	s_waitcnt lgkmcnt(10)
	v_pk_mul_f32 v[2:3], v[32:33], v[212:213]
	v_pk_mul_f32 v[4:5], v[32:33], v[216:217]
	v_pk_mul_f32 v[8:9], v[32:33], v[220:221]
	v_pk_mul_f32 v[10:11], v[32:33], v[224:225]
	v_pk_fma_f32 v[2:3], v[30:31], v[210:211], v[2:3]
	v_pk_fma_f32 v[4:5], v[30:31], v[214:215], v[4:5]
	v_pk_fma_f32 v[8:9], v[30:31], v[218:219], v[8:9]
	v_pk_fma_f32 v[10:11], v[30:31], v[222:223], v[10:11]
	v_add_f32_e32 v12, v2, v3
	v_add_f32_e32 v13, v4, v5
	v_add_f32_e32 v14, v8, v9
	v_add_f32_e32 v15, v10, v11
	v_cndmask_b32_e32 v17, v12, v13, vcc
	v_cndmask_b32_e32 v19, v14, v15, vcc
	v_cndmask_b32_e32 v16, v13, v12, vcc
	v_cndmask_b32_e32 v18, v15, v14, vcc
	v_add_f32_dpp v17, v17, v16 quad_perm:[1,0,3,2] row_mask:0xf bank_mask:0xf bound_ctrl:1
	v_add_f32_dpp v19, v19, v18 quad_perm:[1,0,3,2] row_mask:0xf bank_mask:0xf bound_ctrl:1
	v_cndmask_b32_e64 v16, v19, v17, s[4:5]
	v_cndmask_b32_e64 v18, v17, v19, s[4:5]
	s_waitcnt lgkmcnt(5)
	ds_read_b128 v[164:167], v46 offset:4736
	ds_read_b128 v[168:171], v46 offset:4992
	v_add_f32_dpp v18, v18, v16 quad_perm:[2,3,0,1] row_mask:0xf bank_mask:0xf bound_ctrl:1
	ds_read_b128 v[172:175], v46 offset:5248
	ds_read_b128 v[176:179], v46 offset:5504
	v_add_f32_dpp v18, v18, v18 row_ror:4 row_mask:0xf bank_mask:0xf bound_ctrl:1
	ds_read_b128 v[180:183], v46 offset:5760
	ds_read_b128 v[184:187], v46 offset:6016
	v_add_f32_dpp v20, v18, v18 row_ror:8 row_mask:0xf bank_mask:0xf bound_ctrl:1
	ds_read_b128 v[188:191], v46 offset:6272
	ds_read_b128 v[192:195], v46 offset:6528
	s_waitcnt lgkmcnt(8)
; __device__ void rwscan_item(const Params& p, int l, int item, unsigned char* ldsraw) {
;     ...
; #pragma unroll
;       for (int j = 0; j < 4; ++j) {
;         const f32x2* pb = (const f32x2*)(cb + j * PRF + cg * 4);
;     ...
;         LDV(0, A1a, A1b) LDV(1, A2a, A2b) LDV(2, A3a, A3b) LDV(3, A4a, A4b)
;         LDV(4, U0a, U0b) LDV(5, U1a, U1b) LDV(6, U2a, U2b) LDV(7, U3a, U3b) LDV(8, U4a, U4b)
;     ...
;         const float4 ca = *(const float4*)(cb + j * PRF + 576), cc = *(const float4*)(cb + j * PRF + 580);
;         const float v1 = cb[4 * PRF + (2 * j) * 16 + wave * 4 + rsel];
;         const float v2 = cb[4 * PRF + (2 * j + 1) * 16 + wave * 4 + rsel];
;         f32x2 t1 = sa * A1a + sb * A1b, t2 = sa * A2a + sb * A2b, t3 = sa * A3a + sb * A3b, t4 = sa * A4a + sb * A4b;
;         const float p1 = t1.x + t1.y, p2 = t2.x + t2.y, p3 = t3.x + t3.y, p4 = t4.x + t4.y;
;         const float u12 = (bit0 ? p2 : p1) + dppx<0xB1>(bit0 ? p1 : p2);
;         const float u34 = (bit0 ? p4 : p3) + dppx<0xB1>(bit0 ? p3 : p4);
;         float wq = (bit1 ? u34 : u12) + dppx<0x4E>(bit1 ? u12 : u34);
;         wq += dppx<0x124>(wq);
;         wq += dppx<0x128>(wq);
;         const float d1 = -dppx<0x00>(wq);
;         const float d2 = -(dppx<0x55>(wq) + d1 * ca.x + v1 * ca.y);
;         const float e1 = isy1 ? ca.z : cc.x, e2 = isy1 ? ca.w : cc.y, e3 = isy1 ? 0.f : cc.z, e4 = isy1 ? 0.f : cc.w;
;         yv[j] = wq + d1 * e1 + v1 * e2 + d2 * e3 + v2 * e4;
;         sa = sa * U0a + d1 * U1a + v1 * U2a + d2 * U3a + v2 * U4a;
;         sb = sb * U0b + d1 * U1b + v1 * U2b + d2 * U3b + v2 * U4b;
	v_mov_b32_dpp v246, v20 quad_perm:[0,0,0,0] row_mask:0xf bank_mask:0xf bound_ctrl:1
	v_pk_mul_f32 v[22:23], v[250:251], v[246:247]
	v_pk_mul_f32 v[36:37], v[230:231], v[246:247] op_sel_hi:[1,0] neg_lo:[0,1] neg_hi:[0,1]
	ds_read_b128 v[196:199], v46 offset:6784
	v_pk_mul_f32 v[38:39], v[232:233], v[246:247] op_sel_hi:[1,0] neg_lo:[0,1] neg_hi:[0,1]
	v_sub_f32_dpp v21, v20, v22 quad_perm:[1,1,1,1] row_mask:0xf bank_mask:0xf bound_ctrl:1
	v_fma_f32 v27, -v252, v246, v20
	v_pk_fma_f32 v[36:37], v[30:31], v[226:227], v[36:37]
	v_add_f32_e32 v248, v23, v21
	ds_read_b32 v201, v53 offset:512
	v_pk_fma_f32 v[38:39], v[32:33], v[228:229], v[38:39]
	v_fmac_f32_e32 v27, v247, v253
	v_pk_fma_f32 v[36:37], v[234:235], v[246:247], v[36:37] op_sel:[0,1,0] op_sel_hi:[1,1,1]
	v_pk_fma_f32 v[38:39], v[236:237], v[246:247], v[38:39] op_sel:[0,1,0] op_sel_hi:[1,1,1]
	ds_read_b32 v203, v53 offset:576
	v_fma_f32 v27, -v248, v254, v27
	v_pk_fma_f32 v[36:37], v[238:239], v[248:249], v[36:37] op_sel_hi:[1,0,1] neg_lo:[0,1,0] neg_hi:[0,1,0]
	v_pk_fma_f32 v[38:39], v[240:241], v[248:249], v[38:39] op_sel_hi:[1,0,1] neg_lo:[0,1,0] neg_hi:[0,1,0]
	ds_read_b64 v[204:205], v59 offset:7040
	v_fmac_f32_e32 v27, v249, v255
	v_pk_fma_f32 v[30:31], v[242:243], v[248:249], v[36:37] op_sel:[0,1,0] op_sel_hi:[1,1,1]
	v_pk_fma_f32 v[32:33], v[244:245], v[248:249], v[38:39] op_sel:[0,1,0] op_sel_hi:[1,1,1]
	ds_read_b64 v[206:207], v54 offset:4736
	ds_read_b64 v[208:209], v55 offset:4736
	s_waitcnt lgkmcnt(10)
	v_pk_mul_f32 v[2:3], v[32:33], v[166:167]
	v_pk_mul_f32 v[4:5], v[32:33], v[170:171]
	v_pk_mul_f32 v[8:9], v[32:33], v[174:175]
	v_pk_mul_f32 v[10:11], v[32:33], v[178:179]
	v_pk_fma_f32 v[2:3], v[30:31], v[164:165], v[2:3]
	v_pk_fma_f32 v[4:5], v[30:31], v[168:169], v[4:5]
	v_pk_fma_f32 v[8:9], v[30:31], v[172:173], v[8:9]
	v_pk_fma_f32 v[10:11], v[30:31], v[176:177], v[10:11]
	v_add_f32_e32 v12, v2, v3
	v_add_f32_e32 v13, v4, v5
	v_add_f32_e32 v14, v8, v9
	v_add_f32_e32 v15, v10, v11
	v_cndmask_b32_e32 v17, v12, v13, vcc
	v_cndmask_b32_e32 v19, v14, v15, vcc
	v_cndmask_b32_e32 v16, v13, v12, vcc
	v_cndmask_b32_e32 v18, v15, v14, vcc
	v_add_f32_dpp v17, v17, v16 quad_perm:[1,0,3,2] row_mask:0xf bank_mask:0xf bound_ctrl:1
	v_add_f32_dpp v19, v19, v18 quad_perm:[1,0,3,2] row_mask:0xf bank_mask:0xf bound_ctrl:1
	v_cndmask_b32_e64 v16, v19, v17, s[4:5]
	v_cndmask_b32_e64 v18, v17, v19, s[4:5]
	s_waitcnt lgkmcnt(5)
	ds_read_b128 v[210:213], v46 offset:7104
	ds_read_b128 v[214:217], v46 offset:7360
	v_add_f32_dpp v18, v18, v16 quad_perm:[2,3,0,1] row_mask:0xf bank_mask:0xf bound_ctrl:1
	ds_read_b128 v[218:221], v46 offset:7616
	ds_read_b128 v[222:225], v46 offset:7872
	v_add_f32_dpp v18, v18, v18 row_ror:4 row_mask:0xf bank_mask:0xf bound_ctrl:1
	ds_read_b128 v[226:229], v46 offset:8128
	ds_read_b128 v[230:233], v46 offset:8384
	v_add_f32_dpp v20, v18, v18 row_ror:8 row_mask:0xf bank_mask:0xf bound_ctrl:1
	ds_read_b128 v[234:237], v46 offset:8640
	ds_read_b128 v[238:241], v46 offset:8896
	s_waitcnt lgkmcnt(8)
	v_mov_b32_dpp v200, v20 quad_perm:[0,0,0,0] row_mask:0xf bank_mask:0xf bound_ctrl:1
	v_pk_mul_f32 v[22:23], v[204:205], v[200:201]
	v_pk_mul_f32 v[36:37], v[184:185], v[200:201] op_sel_hi:[1,0] neg_lo:[0,1] neg_hi:[0,1]
	ds_read_b128 v[242:245], v46 offset:9152
	v_pk_mul_f32 v[38:39], v[186:187], v[200:201] op_sel_hi:[1,0] neg_lo:[0,1] neg_hi:[0,1]
	v_sub_f32_dpp v21, v20, v22 quad_perm:[1,1,1,1] row_mask:0xf bank_mask:0xf bound_ctrl:1
	v_fma_f32 v28, -v206, v200, v20
	v_pk_fma_f32 v[36:37], v[30:31], v[180:181], v[36:37]
	v_add_f32_e32 v202, v23, v21
	ds_read_b32 v247, v53 offset:640
	v_pk_fma_f32 v[38:39], v[32:33], v[182:183], v[38:39]
	v_fmac_f32_e32 v28, v201, v207
	v_pk_fma_f32 v[36:37], v[188:189], v[200:201], v[36:37] op_sel:[0,1,0] op_sel_hi:[1,1,1]
	v_pk_fma_f32 v[38:39], v[190:191], v[200:201], v[38:39] op_sel:[0,1,0] op_sel_hi:[1,1,1]
	ds_read_b32 v249, v53 offset:704
	v_fma_f32 v28, -v202, v208, v28
	v_pk_fma_f32 v[36:37], v[192:193], v[202:203], v[36:37] op_sel_hi:[1,0,1] neg_lo:[0,1,0] neg_hi:[0,1,0]
	v_pk_fma_f32 v[38:39], v[194:195], v[202:203], v[38:39] op_sel_hi:[1,0,1] neg_lo:[0,1,0] neg_hi:[0,1,0]
	ds_read_b64 v[250:251], v59 offset:9408
	v_fmac_f32_e32 v28, v203, v209
	v_pk_fma_f32 v[30:31], v[196:197], v[202:203], v[36:37] op_sel:[0,1,0] op_sel_hi:[1,1,1]
	v_pk_fma_f32 v[32:33], v[198:199], v[202:203], v[38:39] op_sel:[0,1,0] op_sel_hi:[1,1,1]
	ds_read_b64 v[252:253], v54 offset:7104
	ds_read_b64 v[254:255], v55 offset:7104
	s_waitcnt lgkmcnt(10)
; __device__ __forceinline__ void lds_barrier() { asm volatile("s_waitcnt lgkmcnt(0)\n\ts_barrier" ::: "memory"); }
; __device__ void rwscan_item(const Params& p, int l, int item, unsigned char* ldsraw) {
;     ...
;         wq += dppx<0x124>(wq);
;         wq += dppx<0x128>(wq);
;         const float d1 = -dppx<0x00>(wq);
;         const float d2 = -(dppx<0x55>(wq) + d1 * ca.x + v1 * ca.y);
;         const float e1 = isy1 ? ca.z : cc.x, e2 = isy1 ? ca.w : cc.y, e3 = isy1 ? 0.f : cc.z, e4 = isy1 ? 0.f : cc.w;
;         yv[j] = wq + d1 * e1 + v1 * e2 + d2 * e3 + v2 * e4;
;         sa = sa * U0a + d1 * U1a + v1 * U2a + d2 * U3a + v2 * U4a;
;         sb = sb * U0b + d1 * U1b + v1 * U2b + d2 * U3b + v2 * U4b;
;       }
;       {
;         float ym = 0.f;
; #pragma unroll
;         for (int jj = 0; jj < 4; ++jj) ym = ((cg >> 2) == jj) ? yv[jj] : ym;
;         if ((cg & 2) != 0) __hip_atomic_store(yl, f2bf(ym), __ATOMIC_RELAXED, __HIP_MEMORY_SCOPE_AGENT);
;         yl += (size_t)TC * D;
;       }
;       if ((ch & 7) == 7) asm volatile("s_waitcnt vmcnt(8)" ::: "memory");
;       lds_barrier();
	v_pk_mul_f32 v[2:3], v[32:33], v[212:213]
	v_pk_mul_f32 v[4:5], v[32:33], v[216:217]
	v_pk_mul_f32 v[8:9], v[32:33], v[220:221]
	v_pk_mul_f32 v[10:11], v[32:33], v[224:225]
	v_pk_fma_f32 v[2:3], v[30:31], v[210:211], v[2:3]
	v_pk_fma_f32 v[4:5], v[30:31], v[214:215], v[4:5]
	v_pk_fma_f32 v[8:9], v[30:31], v[218:219], v[8:9]
	v_pk_fma_f32 v[10:11], v[30:31], v[222:223], v[10:11]
	v_add_f32_e32 v12, v2, v3
	v_add_f32_e32 v13, v4, v5
	v_add_f32_e32 v14, v8, v9
	v_add_f32_e32 v15, v10, v11
	v_cndmask_b32_e32 v17, v12, v13, vcc
	v_cndmask_b32_e32 v19, v14, v15, vcc
	v_cndmask_b32_e32 v16, v13, v12, vcc
	v_cndmask_b32_e32 v18, v15, v14, vcc
	v_add_f32_dpp v17, v17, v16 quad_perm:[1,0,3,2] row_mask:0xf bank_mask:0xf bound_ctrl:1
	v_add_f32_dpp v19, v19, v18 quad_perm:[1,0,3,2] row_mask:0xf bank_mask:0xf bound_ctrl:1
	v_cndmask_b32_e64 v16, v19, v17, s[4:5]
	v_cndmask_b32_e64 v18, v17, v19, s[4:5]
	s_waitcnt lgkmcnt(5)
	s_nop 1
	v_add_f32_dpp v18, v18, v16 quad_perm:[2,3,0,1] row_mask:0xf bank_mask:0xf bound_ctrl:1
	s_nop 1
	v_add_f32_dpp v18, v18, v18 row_ror:4 row_mask:0xf bank_mask:0xf bound_ctrl:1
	s_nop 1
	v_add_f32_dpp v20, v18, v18 row_ror:8 row_mask:0xf bank_mask:0xf bound_ctrl:1
	s_nop 1
	s_waitcnt lgkmcnt(0)
	v_mov_b32_dpp v246, v20 quad_perm:[0,0,0,0] row_mask:0xf bank_mask:0xf bound_ctrl:1
	v_pk_mul_f32 v[22:23], v[250:251], v[246:247]
	v_pk_mul_f32 v[36:37], v[230:231], v[246:247] op_sel_hi:[1,0] neg_lo:[0,1] neg_hi:[0,1]
	v_pk_mul_f32 v[38:39], v[232:233], v[246:247] op_sel_hi:[1,0] neg_lo:[0,1] neg_hi:[0,1]
	v_sub_f32_dpp v21, v20, v22 quad_perm:[1,1,1,1] row_mask:0xf bank_mask:0xf bound_ctrl:1
	v_fma_f32 v29, -v252, v246, v20
	v_pk_fma_f32 v[36:37], v[30:31], v[226:227], v[36:37]
	v_add_f32_e32 v248, v23, v21
	v_pk_fma_f32 v[38:39], v[32:33], v[228:229], v[38:39]
	v_fmac_f32_e32 v29, v247, v253
	v_pk_fma_f32 v[36:37], v[234:235], v[246:247], v[36:37] op_sel:[0,1,0] op_sel_hi:[1,1,1]
	v_pk_fma_f32 v[38:39], v[236:237], v[246:247], v[38:39] op_sel:[0,1,0] op_sel_hi:[1,1,1]
	v_fma_f32 v29, -v248, v254, v29
	v_pk_fma_f32 v[36:37], v[238:239], v[248:249], v[36:37] op_sel_hi:[1,0,1] neg_lo:[0,1,0] neg_hi:[0,1,0]
	v_pk_fma_f32 v[38:39], v[240:241], v[248:249], v[38:39] op_sel_hi:[1,0,1] neg_lo:[0,1,0] neg_hi:[0,1,0]
	v_fmac_f32_e32 v29, v249, v255
	v_pk_fma_f32 v[30:31], v[242:243], v[248:249], v[36:37] op_sel:[0,1,0] op_sel_hi:[1,1,1]
	v_pk_fma_f32 v[32:33], v[244:245], v[248:249], v[38:39] op_sel:[0,1,0] op_sel_hi:[1,1,1]
	v_cndmask_b32_e64 v0, v26, v27, s[14:15]
	v_cndmask_b32_e64 v0, v0, v28, s[12:13]
	v_cndmask_b32_e64 v0, v0, v29, s[10:11]
	v_bfe_u32 v60, v0, 16, 1
	v_add3_u32 v0, v0, v60, s96
	v_lshrrev_b32_e32 v0, 16, v0
	s_and_saveexec_b64 s[22:23], s[6:7]
	global_store_short v[24:25], v0, off sc1
	s_or_b64 exec, exec, s[22:23]
	s_and_b32 s22, s24, 7
	s_cmp_lg_u32 s22, 7
	s_cbranch_scc1 .Lscan_c_nowait
	s_waitcnt vmcnt(8)
.Lscan_c_nowait:
	s_waitcnt lgkmcnt(0)
	s_barrier
	s_add_i32 s24, s24, 1
	v_lshl_add_u64 v[24:25], v[24:25], 0, s[34:35]
	s_cmpk_lg_i32 s24, 0x200
	s_cbranch_scc1 .LBB0_360
	s_branch .LBB0_364

.LBB0_373:
	s_waitcnt vmcnt(9)
	v_mov_b32_e32 v8, v176
	v_mov_b32_e32 v44, v177
	v_mov_b32_e32 v9, v178
	v_mov_b32_e32 v2, v180
	v_mov_b32_e32 v10, v181
	v_mov_b32_e32 v3, v182
	v_lshlrev_b32_e32 v14, 16, v10
	v_lshlrev_b32_e32 v19, 16, v44
	v_and_b32_e32 v4, 0xffff0000, v9
	v_and_b32_e32 v48, 0xffff0000, v10
	v_lshlrev_b32_e32 v49, 16, v3
	v_and_b32_e32 v10, 0xffff0000, v3
	v_mul_f32_e32 v21, v2, v8
	v_mul_f32_e32 v3, v8, v14
	v_and_b32_e32 v46, 0xffff0000, v44
	v_lshlrev_b32_e32 v47, 16, v9
	ds_write2st64_b32 v54, v19, v3 offset0:39 offset1:40
	v_mul_f32_e32 v3, v8, v4
	v_mul_f32_e32 v8, v21, v10
	ds_write2st64_b32 v54, v3, v8 offset0:41 offset1:42
	ds_write_b32 v54, v49 offset:12032
	v_pk_mul_f32 v[8:9], v[14:15], v[46:47] op_sel_hi:[0,1]
	v_pk_mul_f32 v[30:31], v[4:5], v[46:47] op_sel_hi:[0,1]
	v_pk_mul_f32 v[2:3], v[2:3], v[46:47] op_sel_hi:[0,1]
	v_mov_b32_dpp v8, v8 quad_perm:[1,0,3,2] row_mask:0xf bank_mask:0xf bound_ctrl:1
	v_mov_b32_dpp v9, v9 quad_perm:[1,0,3,2] row_mask:0xf bank_mask:0xf bound_ctrl:1
	v_mov_b32_dpp v30, v30 quad_perm:[1,0,3,2] row_mask:0xf bank_mask:0xf bound_ctrl:1
	v_mov_b32_dpp v31, v31 quad_perm:[1,0,3,2] row_mask:0xf bank_mask:0xf bound_ctrl:1
	v_pk_fma_f32 v[8:9], v[14:15], v[46:47], v[8:9] op_sel_hi:[0,1,1]
	v_pk_fma_f32 v[30:31], v[4:5], v[46:47], v[30:31] op_sel_hi:[0,1,1]
	v_pk_mul_f32 v[46:47], v[2:3], v[10:11] op_sel_hi:[1,0]
	v_pk_mul_f32 v[50:51], v[10:11], v[48:49] op_sel_hi:[0,1]
	ds_write2st64_b32 v54, v21, v2 offset0:43 offset1:44
	ds_write2st64_b32 v54, v3, v48 offset0:45 offset1:46
	v_mov_b32_dpp v46, v46 quad_perm:[1,0,3,2] row_mask:0xf bank_mask:0xf bound_ctrl:1
	v_mov_b32_dpp v47, v47 quad_perm:[1,0,3,2] row_mask:0xf bank_mask:0xf bound_ctrl:1
	v_mov_b32_dpp v50, v50 quad_perm:[1,0,3,2] row_mask:0xf bank_mask:0xf bound_ctrl:1
	v_mov_b32_dpp v51, v51 quad_perm:[1,0,3,2] row_mask:0xf bank_mask:0xf bound_ctrl:1
	v_pk_fma_f32 v[2:3], v[2:3], v[10:11], v[46:47] op_sel_hi:[1,0,1]
	v_pk_fma_f32 v[48:49], v[10:11], v[48:49], v[50:51] op_sel_hi:[0,1,1]
	v_add_f32_dpp v8, v8, v8 quad_perm:[2,3,0,1] row_mask:0xf bank_mask:0xf bound_ctrl:1
	v_add_f32_dpp v9, v9, v9 quad_perm:[2,3,0,1] row_mask:0xf bank_mask:0xf bound_ctrl:1
	v_add_f32_dpp v30, v30, v30 quad_perm:[2,3,0,1] row_mask:0xf bank_mask:0xf bound_ctrl:1
	v_add_f32_dpp v31, v31, v31 quad_perm:[2,3,0,1] row_mask:0xf bank_mask:0xf bound_ctrl:1
	v_add_f32_dpp v2, v2, v2 quad_perm:[2,3,0,1] row_mask:0xf bank_mask:0xf bound_ctrl:1
	v_add_f32_dpp v3, v3, v3 quad_perm:[2,3,0,1] row_mask:0xf bank_mask:0xf bound_ctrl:1
	v_add_f32_dpp v48, v48, v48 quad_perm:[2,3,0,1] row_mask:0xf bank_mask:0xf bound_ctrl:1
	v_add_f32_dpp v49, v49, v49 quad_perm:[2,3,0,1] row_mask:0xf bank_mask:0xf bound_ctrl:1
	v_add_f32_dpp v8, v8, v8 row_half_mirror row_mask:0xf bank_mask:0xf bound_ctrl:1
	v_add_f32_dpp v9, v9, v9 row_half_mirror row_mask:0xf bank_mask:0xf bound_ctrl:1
	v_add_f32_dpp v30, v30, v30 row_half_mirror row_mask:0xf bank_mask:0xf bound_ctrl:1
	v_add_f32_dpp v31, v31, v31 row_half_mirror row_mask:0xf bank_mask:0xf bound_ctrl:1
	v_add_f32_dpp v2, v2, v2 row_half_mirror row_mask:0xf bank_mask:0xf bound_ctrl:1
	v_add_f32_dpp v3, v3, v3 row_half_mirror row_mask:0xf bank_mask:0xf bound_ctrl:1
	v_add_f32_dpp v48, v48, v48 row_half_mirror row_mask:0xf bank_mask:0xf bound_ctrl:1
	v_add_f32_dpp v49, v49, v49 row_half_mirror row_mask:0xf bank_mask:0xf bound_ctrl:1
	v_add_f32_dpp v8, v8, v8 row_ror:8 row_mask:0xf bank_mask:0xf bound_ctrl:1
	v_add_f32_dpp v9, v9, v9 row_ror:8 row_mask:0xf bank_mask:0xf bound_ctrl:1
	v_add_f32_dpp v30, v30, v30 row_ror:8 row_mask:0xf bank_mask:0xf bound_ctrl:1
	v_add_f32_dpp v31, v31, v31 row_ror:8 row_mask:0xf bank_mask:0xf bound_ctrl:1
	v_add_f32_dpp v2, v2, v2 row_ror:8 row_mask:0xf bank_mask:0xf bound_ctrl:1
	v_add_f32_dpp v3, v3, v3 row_ror:8 row_mask:0xf bank_mask:0xf bound_ctrl:1
	v_add_f32_dpp v48, v48, v48 row_ror:8 row_mask:0xf bank_mask:0xf bound_ctrl:1
	v_add_f32_dpp v49, v49, v49 row_ror:8 row_mask:0xf bank_mask:0xf bound_ctrl:1
	v_add_f32_dpp v8, v8, v8 row_bcast:15 row_mask:0xf bank_mask:0xf bound_ctrl:1
	v_add_f32_dpp v9, v9, v9 row_bcast:15 row_mask:0xf bank_mask:0xf bound_ctrl:1
	v_add_f32_dpp v30, v30, v30 row_bcast:15 row_mask:0xf bank_mask:0xf bound_ctrl:1
	v_add_f32_dpp v31, v31, v31 row_bcast:15 row_mask:0xf bank_mask:0xf bound_ctrl:1
	v_add_f32_dpp v2, v2, v2 row_bcast:15 row_mask:0xf bank_mask:0xf bound_ctrl:1
	v_add_f32_dpp v3, v3, v3 row_bcast:15 row_mask:0xf bank_mask:0xf bound_ctrl:1
	v_add_f32_dpp v48, v48, v48 row_bcast:15 row_mask:0xf bank_mask:0xf bound_ctrl:1
	v_add_f32_dpp v49, v49, v49 row_bcast:15 row_mask:0xf bank_mask:0xf bound_ctrl:1
	s_mov_b32 s15, s16
	v_add_f32_dpp v8, v8, v8 row_bcast:31 row_mask:0xf bank_mask:0xf bound_ctrl:1
	v_add_f32_dpp v9, v9, v9 row_bcast:31 row_mask:0xf bank_mask:0xf bound_ctrl:1
	v_add_f32_dpp v30, v30, v30 row_bcast:31 row_mask:0xf bank_mask:0xf bound_ctrl:1
	v_add_f32_dpp v31, v31, v31 row_bcast:31 row_mask:0xf bank_mask:0xf bound_ctrl:1
	v_add_f32_dpp v2, v2, v2 row_bcast:31 row_mask:0xf bank_mask:0xf bound_ctrl:1
	v_add_f32_dpp v3, v3, v3 row_bcast:31 row_mask:0xf bank_mask:0xf bound_ctrl:1
	v_add_f32_dpp v48, v48, v48 row_bcast:31 row_mask:0xf bank_mask:0xf bound_ctrl:1
	v_add_f32_dpp v49, v49, v49 row_bcast:31 row_mask:0xf bank_mask:0xf bound_ctrl:1
	s_and_saveexec_b64 s[10:11], s[4:5]
	s_cbranch_execz .LBB0_375
	ds_write_b64 v53, v[8:9] offset:12288
	ds_write_b64 v53, v[30:31] offset:12296
	ds_write_b64 v53, v[2:3] offset:12304
	ds_write_b64 v53, v[48:49] offset:12312

.Lscan_ld_nochk:
	s_min_u32 s10, s15, 0x1fa
	s_mulk_i32 s10, 0xc00
	s_addk_i32 s10, 0x3c00
	s_mul_i32 s98, s10, 12
	v_lshl_add_u64 v[2:3], v[36:37], 0, s[98:99]
	v_add_co_u32_e32 v22, vcc, 0x1000, v2
	s_lshl_b32 s98, s10, 1
	s_nop 0
	v_addc_co_u32_e32 v23, vcc, 0, v3, vcc
	global_load_dwordx3 v[176:178], v[2:3], off
	s_nop 0
	global_load_dwordx3 v[180:182], v[22:23], off offset:512
	v_lshl_add_u64 v[22:23], v[38:39], 0, s[98:99]
	global_load_ushort v55, v[22:23], off
	s_waitcnt vmcnt(9)
	v_mov_b32_e32 v16, v184
	v_mov_b32_e32 v42, v185
	v_mov_b32_e32 v17, v186
	v_mov_b32_e32 v12, v188
	v_mov_b32_e32 v18, v189
	v_mov_b32_e32 v13, v190
	v_lshlrev_b32_e32 v22, 16, v18
	v_lshlrev_b32_e32 v19, 16, v42
	v_and_b32_e32 v14, 0xffff0000, v17
	v_lshlrev_b32_e32 v45, 16, v13
	v_and_b32_e32 v46, 0xffff0000, v13
	v_mul_f32_e32 v21, v12, v16
	v_mul_f32_e32 v13, v16, v22
	s_waitcnt lgkmcnt(0)
	s_barrier
	v_and_b32_e32 v42, 0xffff0000, v42
	v_lshlrev_b32_e32 v43, 16, v17
	ds_write2st64_b32 v54, v19, v13 offset1:1
	v_mul_f32_e32 v13, v16, v14
	v_mul_f32_e32 v16, v21, v46
	ds_write2st64_b32 v54, v13, v16 offset0:2 offset1:3
	ds_write_b32 v54, v45 offset:2048
	v_pk_mul_f32 v[16:17], v[22:23], v[42:43] op_sel_hi:[0,1]
	v_and_b32_e32 v44, 0xffff0000, v18
	v_pk_mul_f32 v[12:13], v[12:13], v[42:43] op_sel_hi:[0,1]
	v_mov_b32_dpp v16, v16 quad_perm:[1,0,3,2] row_mask:0xf bank_mask:0xf bound_ctrl:1
	v_mov_b32_dpp v17, v17 quad_perm:[1,0,3,2] row_mask:0xf bank_mask:0xf bound_ctrl:1
	v_pk_fma_f32 v[16:17], v[22:23], v[42:43], v[16:17] op_sel_hi:[0,1,1]
	v_pk_mul_f32 v[22:23], v[14:15], v[42:43] op_sel_hi:[0,1]
	v_pk_mul_f32 v[48:49], v[46:47], v[44:45] op_sel_hi:[0,1]
	ds_write2st64_b32 v54, v21, v12 offset0:4 offset1:5
	ds_write2st64_b32 v54, v13, v44 offset0:6 offset1:7
	v_mov_b32_dpp v22, v22 quad_perm:[1,0,3,2] row_mask:0xf bank_mask:0xf bound_ctrl:1
	v_mov_b32_dpp v23, v23 quad_perm:[1,0,3,2] row_mask:0xf bank_mask:0xf bound_ctrl:1
	v_pk_fma_f32 v[22:23], v[14:15], v[42:43], v[22:23] op_sel_hi:[0,1,1]
	v_pk_mul_f32 v[42:43], v[12:13], v[46:47] op_sel_hi:[1,0]
	v_mov_b32_dpp v48, v48 quad_perm:[1,0,3,2] row_mask:0xf bank_mask:0xf bound_ctrl:1
	v_mov_b32_dpp v49, v49 quad_perm:[1,0,3,2] row_mask:0xf bank_mask:0xf bound_ctrl:1
	v_mov_b32_dpp v42, v42 quad_perm:[1,0,3,2] row_mask:0xf bank_mask:0xf bound_ctrl:1
	v_mov_b32_dpp v43, v43 quad_perm:[1,0,3,2] row_mask:0xf bank_mask:0xf bound_ctrl:1
	v_pk_fma_f32 v[12:13], v[12:13], v[46:47], v[42:43] op_sel_hi:[1,0,1]
	v_pk_fma_f32 v[44:45], v[46:47], v[44:45], v[48:49] op_sel_hi:[0,1,1]
	v_add_f32_dpp v16, v16, v16 quad_perm:[2,3,0,1] row_mask:0xf bank_mask:0xf bound_ctrl:1
	v_add_f32_dpp v17, v17, v17 quad_perm:[2,3,0,1] row_mask:0xf bank_mask:0xf bound_ctrl:1
	v_add_f32_dpp v22, v22, v22 quad_perm:[2,3,0,1] row_mask:0xf bank_mask:0xf bound_ctrl:1
	v_add_f32_dpp v23, v23, v23 quad_perm:[2,3,0,1] row_mask:0xf bank_mask:0xf bound_ctrl:1
	v_add_f32_dpp v12, v12, v12 quad_perm:[2,3,0,1] row_mask:0xf bank_mask:0xf bound_ctrl:1
	v_add_f32_dpp v13, v13, v13 quad_perm:[2,3,0,1] row_mask:0xf bank_mask:0xf bound_ctrl:1
	v_add_f32_dpp v44, v44, v44 quad_perm:[2,3,0,1] row_mask:0xf bank_mask:0xf bound_ctrl:1
	v_add_f32_dpp v45, v45, v45 quad_perm:[2,3,0,1] row_mask:0xf bank_mask:0xf bound_ctrl:1
	v_add_f32_dpp v16, v16, v16 row_half_mirror row_mask:0xf bank_mask:0xf bound_ctrl:1
	v_add_f32_dpp v17, v17, v17 row_half_mirror row_mask:0xf bank_mask:0xf bound_ctrl:1
	v_add_f32_dpp v22, v22, v22 row_half_mirror row_mask:0xf bank_mask:0xf bound_ctrl:1
	v_add_f32_dpp v23, v23, v23 row_half_mirror row_mask:0xf bank_mask:0xf bound_ctrl:1
	v_add_f32_dpp v12, v12, v12 row_half_mirror row_mask:0xf bank_mask:0xf bound_ctrl:1
	v_add_f32_dpp v13, v13, v13 row_half_mirror row_mask:0xf bank_mask:0xf bound_ctrl:1
	v_add_f32_dpp v44, v44, v44 row_half_mirror row_mask:0xf bank_mask:0xf bound_ctrl:1
	v_add_f32_dpp v45, v45, v45 row_half_mirror row_mask:0xf bank_mask:0xf bound_ctrl:1
	v_add_f32_dpp v16, v16, v16 row_ror:8 row_mask:0xf bank_mask:0xf bound_ctrl:1
	v_add_f32_dpp v17, v17, v17 row_ror:8 row_mask:0xf bank_mask:0xf bound_ctrl:1
	v_add_f32_dpp v22, v22, v22 row_ror:8 row_mask:0xf bank_mask:0xf bound_ctrl:1
	v_add_f32_dpp v23, v23, v23 row_ror:8 row_mask:0xf bank_mask:0xf bound_ctrl:1
	v_add_f32_dpp v12, v12, v12 row_ror:8 row_mask:0xf bank_mask:0xf bound_ctrl:1
	v_add_f32_dpp v13, v13, v13 row_ror:8 row_mask:0xf bank_mask:0xf bound_ctrl:1
	v_add_f32_dpp v44, v44, v44 row_ror:8 row_mask:0xf bank_mask:0xf bound_ctrl:1
	v_add_f32_dpp v45, v45, v45 row_ror:8 row_mask:0xf bank_mask:0xf bound_ctrl:1
	v_add_f32_dpp v16, v16, v16 row_bcast:15 row_mask:0xf bank_mask:0xf bound_ctrl:1
	v_add_f32_dpp v17, v17, v17 row_bcast:15 row_mask:0xf bank_mask:0xf bound_ctrl:1
	v_add_f32_dpp v22, v22, v22 row_bcast:15 row_mask:0xf bank_mask:0xf bound_ctrl:1
	v_add_f32_dpp v23, v23, v23 row_bcast:15 row_mask:0xf bank_mask:0xf bound_ctrl:1
	v_add_f32_dpp v12, v12, v12 row_bcast:15 row_mask:0xf bank_mask:0xf bound_ctrl:1
	v_add_f32_dpp v13, v13, v13 row_bcast:15 row_mask:0xf bank_mask:0xf bound_ctrl:1
	v_add_f32_dpp v44, v44, v44 row_bcast:15 row_mask:0xf bank_mask:0xf bound_ctrl:1
	v_add_f32_dpp v45, v45, v45 row_bcast:15 row_mask:0xf bank_mask:0xf bound_ctrl:1
	v_add_f32_dpp v16, v16, v16 row_bcast:31 row_mask:0xf bank_mask:0xf bound_ctrl:1
	v_add_f32_dpp v17, v17, v17 row_bcast:31 row_mask:0xf bank_mask:0xf bound_ctrl:1
	v_add_f32_dpp v22, v22, v22 row_bcast:31 row_mask:0xf bank_mask:0xf bound_ctrl:1
	v_add_f32_dpp v23, v23, v23 row_bcast:31 row_mask:0xf bank_mask:0xf bound_ctrl:1
	v_add_f32_dpp v12, v12, v12 row_bcast:31 row_mask:0xf bank_mask:0xf bound_ctrl:1
	v_add_f32_dpp v13, v13, v13 row_bcast:31 row_mask:0xf bank_mask:0xf bound_ctrl:1
	v_add_f32_dpp v44, v44, v44 row_bcast:31 row_mask:0xf bank_mask:0xf bound_ctrl:1
	v_add_f32_dpp v45, v45, v45 row_bcast:31 row_mask:0xf bank_mask:0xf bound_ctrl:1
	s_and_saveexec_b64 s[10:11], s[4:5]
	s_cbranch_execz .LBB0_379
	ds_write_b64 v53, v[16:17] offset:2304
	ds_write_b64 v53, v[22:23] offset:2312
	ds_write_b64 v53, v[12:13] offset:2320
	ds_write_b64 v53, v[44:45] offset:2328
.LBB0_379:
	s_or_b64 exec, exec, s[10:11]
	s_and_saveexec_b64 s[10:11], s[6:7]
	v_lshlrev_b32_e32 v12, 16, v56
	ds_write_b32 v58, v12 offset:9472
	s_or_b64 exec, exec, s[10:11]
	s_min_u32 s10, s15, 0x1f9
	s_mulk_i32 s10, 0xc00
	s_addk_i32 s10, 0x4800
	s_mul_i32 s98, s10, 12
	v_lshl_add_u64 v[12:13], v[36:37], 0, s[98:99]
	v_add_co_u32_e32 v22, vcc, 0x1000, v12
	s_lshl_b32 s98, s10, 1
	s_nop 0
	v_addc_co_u32_e32 v23, vcc, 0, v13, vcc
	global_load_dwordx3 v[184:186], v[12:13], off
	s_nop 0
	global_load_dwordx3 v[188:190], v[22:23], off offset:512
	v_lshl_add_u64 v[22:23], v[38:39], 0, s[98:99]
	global_load_ushort v56, v[22:23], off
	s_waitcnt vmcnt(9)
	v_mov_b32_e32 v24, v192
	v_mov_b32_e32 v40, v193
	v_mov_b32_e32 v11, v194
	v_mov_b32_e32 v20, v196
	v_mov_b32_e32 v26, v197
	v_mov_b32_e32 v15, v198
	v_lshlrev_b32_e32 v22, 16, v26
	v_lshlrev_b32_e32 v19, 16, v40
	v_and_b32_e32 v40, 0xffff0000, v40
	v_lshlrev_b32_e32 v41, 16, v11
	v_and_b32_e32 v30, 0xffff0000, v11
	v_lshlrev_b32_e32 v43, 16, v15
	v_and_b32_e32 v44, 0xffff0000, v15
	v_mul_f32_e32 v15, v24, v22
	s_waitcnt lgkmcnt(0)
	s_barrier
	v_and_b32_e32 v42, 0xffff0000, v26
	v_mul_f32_e32 v11, v20, v24
	ds_write2st64_b32 v54, v19, v15 offset0:39 offset1:40
	v_mul_f32_e32 v15, v24, v30
	v_pk_mul_f32 v[24:25], v[22:23], v[40:41] op_sel_hi:[0,1]
	v_pk_mul_f32 v[26:27], v[30:31], v[40:41] op_sel_hi:[0,1]
	v_pk_mul_f32 v[20:21], v[20:21], v[40:41] op_sel_hi:[0,1]
	v_mov_b32_dpp v24, v24 quad_perm:[1,0,3,2] row_mask:0xf bank_mask:0xf bound_ctrl:1
	v_mov_b32_dpp v25, v25 quad_perm:[1,0,3,2] row_mask:0xf bank_mask:0xf bound_ctrl:1
	v_mov_b32_dpp v26, v26 quad_perm:[1,0,3,2] row_mask:0xf bank_mask:0xf bound_ctrl:1
	v_mov_b32_dpp v27, v27 quad_perm:[1,0,3,2] row_mask:0xf bank_mask:0xf bound_ctrl:1
	v_pk_fma_f32 v[22:23], v[22:23], v[40:41], v[24:25] op_sel_hi:[0,1,1]
	v_pk_fma_f32 v[26:27], v[30:31], v[40:41], v[26:27] op_sel_hi:[0,1,1]
	v_pk_mul_f32 v[40:41], v[20:21], v[44:45] op_sel_hi:[1,0]
	v_pk_mul_f32 v[46:47], v[44:45], v[42:43] op_sel_hi:[0,1]
	v_mul_f32_e32 v19, v11, v44
	v_mov_b32_dpp v40, v40 quad_perm:[1,0,3,2] row_mask:0xf bank_mask:0xf bound_ctrl:1
	v_mov_b32_dpp v41, v41 quad_perm:[1,0,3,2] row_mask:0xf bank_mask:0xf bound_ctrl:1
	v_mov_b32_dpp v46, v46 quad_perm:[1,0,3,2] row_mask:0xf bank_mask:0xf bound_ctrl:1
	v_mov_b32_dpp v47, v47 quad_perm:[1,0,3,2] row_mask:0xf bank_mask:0xf bound_ctrl:1
	ds_write2st64_b32 v54, v15, v19 offset0:41 offset1:42
	ds_write_b32 v54, v43 offset:12032
	ds_write2st64_b32 v54, v11, v20 offset0:43 offset1:44
	ds_write2st64_b32 v54, v21, v42 offset0:45 offset1:46
	v_pk_fma_f32 v[20:21], v[20:21], v[44:45], v[40:41] op_sel_hi:[1,0,1]
	v_pk_fma_f32 v[42:43], v[44:45], v[42:43], v[46:47] op_sel_hi:[0,1,1]
	v_add_f32_dpp v22, v22, v22 quad_perm:[2,3,0,1] row_mask:0xf bank_mask:0xf bound_ctrl:1
	v_add_f32_dpp v23, v23, v23 quad_perm:[2,3,0,1] row_mask:0xf bank_mask:0xf bound_ctrl:1
	v_add_f32_dpp v26, v26, v26 quad_perm:[2,3,0,1] row_mask:0xf bank_mask:0xf bound_ctrl:1
	v_add_f32_dpp v27, v27, v27 quad_perm:[2,3,0,1] row_mask:0xf bank_mask:0xf bound_ctrl:1
	v_add_f32_dpp v20, v20, v20 quad_perm:[2,3,0,1] row_mask:0xf bank_mask:0xf bound_ctrl:1
	v_add_f32_dpp v21, v21, v21 quad_perm:[2,3,0,1] row_mask:0xf bank_mask:0xf bound_ctrl:1
	v_add_f32_dpp v42, v42, v42 quad_perm:[2,3,0,1] row_mask:0xf bank_mask:0xf bound_ctrl:1
	v_add_f32_dpp v43, v43, v43 quad_perm:[2,3,0,1] row_mask:0xf bank_mask:0xf bound_ctrl:1
	v_add_f32_dpp v22, v22, v22 row_half_mirror row_mask:0xf bank_mask:0xf bound_ctrl:1
	v_add_f32_dpp v23, v23, v23 row_half_mirror row_mask:0xf bank_mask:0xf bound_ctrl:1
	v_add_f32_dpp v26, v26, v26 row_half_mirror row_mask:0xf bank_mask:0xf bound_ctrl:1
	v_add_f32_dpp v27, v27, v27 row_half_mirror row_mask:0xf bank_mask:0xf bound_ctrl:1
	v_add_f32_dpp v20, v20, v20 row_half_mirror row_mask:0xf bank_mask:0xf bound_ctrl:1
	v_add_f32_dpp v21, v21, v21 row_half_mirror row_mask:0xf bank_mask:0xf bound_ctrl:1
	v_add_f32_dpp v42, v42, v42 row_half_mirror row_mask:0xf bank_mask:0xf bound_ctrl:1
	v_add_f32_dpp v43, v43, v43 row_half_mirror row_mask:0xf bank_mask:0xf bound_ctrl:1
	v_add_f32_dpp v22, v22, v22 row_ror:8 row_mask:0xf bank_mask:0xf bound_ctrl:1
	v_add_f32_dpp v23, v23, v23 row_ror:8 row_mask:0xf bank_mask:0xf bound_ctrl:1
	v_add_f32_dpp v26, v26, v26 row_ror:8 row_mask:0xf bank_mask:0xf bound_ctrl:1
	v_add_f32_dpp v27, v27, v27 row_ror:8 row_mask:0xf bank_mask:0xf bound_ctrl:1
	v_add_f32_dpp v20, v20, v20 row_ror:8 row_mask:0xf bank_mask:0xf bound_ctrl:1
	v_add_f32_dpp v21, v21, v21 row_ror:8 row_mask:0xf bank_mask:0xf bound_ctrl:1
	v_add_f32_dpp v42, v42, v42 row_ror:8 row_mask:0xf bank_mask:0xf bound_ctrl:1
	v_add_f32_dpp v43, v43, v43 row_ror:8 row_mask:0xf bank_mask:0xf bound_ctrl:1
	v_add_f32_dpp v22, v22, v22 row_bcast:15 row_mask:0xf bank_mask:0xf bound_ctrl:1
	v_add_f32_dpp v23, v23, v23 row_bcast:15 row_mask:0xf bank_mask:0xf bound_ctrl:1
	v_add_f32_dpp v26, v26, v26 row_bcast:15 row_mask:0xf bank_mask:0xf bound_ctrl:1
	v_add_f32_dpp v27, v27, v27 row_bcast:15 row_mask:0xf bank_mask:0xf bound_ctrl:1
	v_add_f32_dpp v20, v20, v20 row_bcast:15 row_mask:0xf bank_mask:0xf bound_ctrl:1
	v_add_f32_dpp v21, v21, v21 row_bcast:15 row_mask:0xf bank_mask:0xf bound_ctrl:1
	v_add_f32_dpp v42, v42, v42 row_bcast:15 row_mask:0xf bank_mask:0xf bound_ctrl:1
	v_add_f32_dpp v43, v43, v43 row_bcast:15 row_mask:0xf bank_mask:0xf bound_ctrl:1
	v_add_f32_dpp v22, v22, v22 row_bcast:31 row_mask:0xf bank_mask:0xf bound_ctrl:1
	v_add_f32_dpp v23, v23, v23 row_bcast:31 row_mask:0xf bank_mask:0xf bound_ctrl:1
	v_add_f32_dpp v26, v26, v26 row_bcast:31 row_mask:0xf bank_mask:0xf bound_ctrl:1
	v_add_f32_dpp v27, v27, v27 row_bcast:31 row_mask:0xf bank_mask:0xf bound_ctrl:1
	v_add_f32_dpp v20, v20, v20 row_bcast:31 row_mask:0xf bank_mask:0xf bound_ctrl:1
	v_add_f32_dpp v21, v21, v21 row_bcast:31 row_mask:0xf bank_mask:0xf bound_ctrl:1
	v_add_f32_dpp v42, v42, v42 row_bcast:31 row_mask:0xf bank_mask:0xf bound_ctrl:1
	v_add_f32_dpp v43, v43, v43 row_bcast:31 row_mask:0xf bank_mask:0xf bound_ctrl:1
	s_and_saveexec_b64 s[10:11], s[4:5]
	s_cbranch_execz .LBB0_383
	ds_write_b64 v53, v[22:23] offset:12288
	ds_write_b64 v53, v[26:27] offset:12296
	ds_write_b64 v53, v[20:21] offset:12304
	ds_write_b64 v53, v[42:43] offset:12312
.LBB0_383:
	s_or_b64 exec, exec, s[10:11]
	s_and_saveexec_b64 s[10:11], s[6:7]
	v_lshlrev_b32_e32 v11, 16, v57
	ds_write_b32 v58, v11 offset:19456
	s_or_b64 exec, exec, s[10:11]
	s_add_i32 s22, s15, 4
	s_min_u32 s22, s22, 0x1f7
	s_add_i32 s22, s22, 8
	s_lshr_b32 s22, s22, 3
	s_lshl_b32 s22, s22, 2
	v_mov_b32_e32 v201, s22
	global_load_dword v200, v201, s[18:19] offset:2048 sc1
	s_min_u32 s10, s15, 0x1f8
	s_mulk_i32 s10, 0xc00
	s_addk_i32 s10, 0x5400
	s_mul_i32 s98, s10, 12
	v_lshl_add_u64 v[20:21], v[36:37], 0, s[98:99]
	s_lshl_b32 s98, s10, 1
	v_add_co_u32_e32 v22, vcc, 0x1000, v20
	v_lshl_add_u64 v[30:31], v[38:39], 0, s[98:99]
	s_nop 0
	v_addc_co_u32_e32 v23, vcc, 0, v21, vcc
	global_load_dwordx3 v[192:194], v[20:21], off
	s_nop 0
	global_load_dwordx3 v[196:198], v[22:23], off offset:512
	global_load_ushort v57, v[30:31], off
	s_waitcnt vmcnt(9)
	v_mov_b32_e32 v32, v168
	v_mov_b32_e32 v0, v169
	v_mov_b32_e32 v5, v170
	v_mov_b32_e32 v28, v172
	v_mov_b32_e32 v34, v173
	v_mov_b32_e32 v7, v174
	v_lshlrev_b32_e32 v11, 16, v0
	v_lshlrev_b32_e32 v30, 16, v34
	v_and_b32_e32 v42, 0xffff0000, v0
	v_lshlrev_b32_e32 v43, 16, v5
	v_and_b32_e32 v0, 0xffff0000, v5
	v_lshlrev_b32_e32 v45, 16, v7
	v_and_b32_e32 v46, 0xffff0000, v7
	v_mul_f32_e32 v7, v32, v30
	s_waitcnt lgkmcnt(0)
	s_barrier
	v_and_b32_e32 v44, 0xffff0000, v34
	v_mul_f32_e32 v5, v28, v32
	ds_write2st64_b32 v54, v11, v7 offset1:1
	v_mul_f32_e32 v7, v32, v0
	v_pk_mul_f32 v[32:33], v[30:31], v[42:43] op_sel_hi:[0,1]
	v_pk_mul_f32 v[34:35], v[0:1], v[42:43] op_sel_hi:[0,1]
	v_pk_mul_f32 v[28:29], v[28:29], v[42:43] op_sel_hi:[0,1]
	v_mov_b32_dpp v32, v32 quad_perm:[1,0,3,2] row_mask:0xf bank_mask:0xf bound_ctrl:1
	v_mov_b32_dpp v33, v33 quad_perm:[1,0,3,2] row_mask:0xf bank_mask:0xf bound_ctrl:1
	v_mov_b32_dpp v34, v34 quad_perm:[1,0,3,2] row_mask:0xf bank_mask:0xf bound_ctrl:1
	v_mov_b32_dpp v35, v35 quad_perm:[1,0,3,2] row_mask:0xf bank_mask:0xf bound_ctrl:1
	v_pk_fma_f32 v[30:31], v[30:31], v[42:43], v[32:33] op_sel_hi:[0,1,1]
	v_pk_fma_f32 v[34:35], v[0:1], v[42:43], v[34:35] op_sel_hi:[0,1,1]
	v_pk_mul_f32 v[42:43], v[28:29], v[46:47] op_sel_hi:[1,0]
	v_pk_mul_f32 v[48:49], v[46:47], v[44:45] op_sel_hi:[0,1]
	v_mul_f32_e32 v11, v5, v46
	v_mov_b32_dpp v42, v42 quad_perm:[1,0,3,2] row_mask:0xf bank_mask:0xf bound_ctrl:1
	v_mov_b32_dpp v43, v43 quad_perm:[1,0,3,2] row_mask:0xf bank_mask:0xf bound_ctrl:1
	v_mov_b32_dpp v48, v48 quad_perm:[1,0,3,2] row_mask:0xf bank_mask:0xf bound_ctrl:1
	v_mov_b32_dpp v49, v49 quad_perm:[1,0,3,2] row_mask:0xf bank_mask:0xf bound_ctrl:1
	ds_write2st64_b32 v54, v7, v11 offset0:2 offset1:3
	ds_write_b32 v54, v45 offset:2048
	ds_write2st64_b32 v54, v5, v28 offset0:4 offset1:5
	ds_write2st64_b32 v54, v29, v44 offset0:6 offset1:7
	v_pk_fma_f32 v[28:29], v[28:29], v[46:47], v[42:43] op_sel_hi:[1,0,1]
	v_pk_fma_f32 v[44:45], v[46:47], v[44:45], v[48:49] op_sel_hi:[0,1,1]
	v_add_f32_dpp v30, v30, v30 quad_perm:[2,3,0,1] row_mask:0xf bank_mask:0xf bound_ctrl:1
	v_add_f32_dpp v31, v31, v31 quad_perm:[2,3,0,1] row_mask:0xf bank_mask:0xf bound_ctrl:1
	v_add_f32_dpp v34, v34, v34 quad_perm:[2,3,0,1] row_mask:0xf bank_mask:0xf bound_ctrl:1
	v_add_f32_dpp v35, v35, v35 quad_perm:[2,3,0,1] row_mask:0xf bank_mask:0xf bound_ctrl:1
	v_add_f32_dpp v28, v28, v28 quad_perm:[2,3,0,1] row_mask:0xf bank_mask:0xf bound_ctrl:1
	v_add_f32_dpp v29, v29, v29 quad_perm:[2,3,0,1] row_mask:0xf bank_mask:0xf bound_ctrl:1
	v_add_f32_dpp v44, v44, v44 quad_perm:[2,3,0,1] row_mask:0xf bank_mask:0xf bound_ctrl:1
	v_add_f32_dpp v45, v45, v45 quad_perm:[2,3,0,1] row_mask:0xf bank_mask:0xf bound_ctrl:1
	v_add_f32_dpp v30, v30, v30 row_half_mirror row_mask:0xf bank_mask:0xf bound_ctrl:1
	v_add_f32_dpp v31, v31, v31 row_half_mirror row_mask:0xf bank_mask:0xf bound_ctrl:1
	v_add_f32_dpp v34, v34, v34 row_half_mirror row_mask:0xf bank_mask:0xf bound_ctrl:1
	v_add_f32_dpp v35, v35, v35 row_half_mirror row_mask:0xf bank_mask:0xf bound_ctrl:1
	v_add_f32_dpp v28, v28, v28 row_half_mirror row_mask:0xf bank_mask:0xf bound_ctrl:1
	v_add_f32_dpp v29, v29, v29 row_half_mirror row_mask:0xf bank_mask:0xf bound_ctrl:1
	v_add_f32_dpp v44, v44, v44 row_half_mirror row_mask:0xf bank_mask:0xf bound_ctrl:1
	v_add_f32_dpp v45, v45, v45 row_half_mirror row_mask:0xf bank_mask:0xf bound_ctrl:1
	v_add_f32_dpp v30, v30, v30 row_ror:8 row_mask:0xf bank_mask:0xf bound_ctrl:1
	v_add_f32_dpp v31, v31, v31 row_ror:8 row_mask:0xf bank_mask:0xf bound_ctrl:1
	v_add_f32_dpp v34, v34, v34 row_ror:8 row_mask:0xf bank_mask:0xf bound_ctrl:1
	v_add_f32_dpp v35, v35, v35 row_ror:8 row_mask:0xf bank_mask:0xf bound_ctrl:1
	v_add_f32_dpp v28, v28, v28 row_ror:8 row_mask:0xf bank_mask:0xf bound_ctrl:1
	v_add_f32_dpp v29, v29, v29 row_ror:8 row_mask:0xf bank_mask:0xf bound_ctrl:1
	v_add_f32_dpp v44, v44, v44 row_ror:8 row_mask:0xf bank_mask:0xf bound_ctrl:1
	v_add_f32_dpp v45, v45, v45 row_ror:8 row_mask:0xf bank_mask:0xf bound_ctrl:1
	v_add_f32_dpp v30, v30, v30 row_bcast:15 row_mask:0xf bank_mask:0xf bound_ctrl:1
	v_add_f32_dpp v31, v31, v31 row_bcast:15 row_mask:0xf bank_mask:0xf bound_ctrl:1
	v_add_f32_dpp v34, v34, v34 row_bcast:15 row_mask:0xf bank_mask:0xf bound_ctrl:1
	v_add_f32_dpp v35, v35, v35 row_bcast:15 row_mask:0xf bank_mask:0xf bound_ctrl:1
	v_add_f32_dpp v28, v28, v28 row_bcast:15 row_mask:0xf bank_mask:0xf bound_ctrl:1
	v_add_f32_dpp v29, v29, v29 row_bcast:15 row_mask:0xf bank_mask:0xf bound_ctrl:1
	v_add_f32_dpp v44, v44, v44 row_bcast:15 row_mask:0xf bank_mask:0xf bound_ctrl:1
	v_add_f32_dpp v45, v45, v45 row_bcast:15 row_mask:0xf bank_mask:0xf bound_ctrl:1
	v_add_f32_dpp v30, v30, v30 row_bcast:31 row_mask:0xf bank_mask:0xf bound_ctrl:1
	v_add_f32_dpp v31, v31, v31 row_bcast:31 row_mask:0xf bank_mask:0xf bound_ctrl:1
	v_add_f32_dpp v34, v34, v34 row_bcast:31 row_mask:0xf bank_mask:0xf bound_ctrl:1
	v_add_f32_dpp v35, v35, v35 row_bcast:31 row_mask:0xf bank_mask:0xf bound_ctrl:1
	v_add_f32_dpp v28, v28, v28 row_bcast:31 row_mask:0xf bank_mask:0xf bound_ctrl:1
	v_add_f32_dpp v29, v29, v29 row_bcast:31 row_mask:0xf bank_mask:0xf bound_ctrl:1
	v_add_f32_dpp v44, v44, v44 row_bcast:31 row_mask:0xf bank_mask:0xf bound_ctrl:1
	v_add_f32_dpp v45, v45, v45 row_bcast:31 row_mask:0xf bank_mask:0xf bound_ctrl:1
	s_and_saveexec_b64 s[10:11], s[4:5]
	s_cbranch_execz .LBB0_387
	ds_write_b64 v53, v[30:31] offset:2304
	ds_write_b64 v53, v[34:35] offset:2312
	ds_write_b64 v53, v[28:29] offset:2320
	ds_write_b64 v53, v[44:45] offset:2328

; template <bool COOP>
; __global__ void __launch_bounds__(NT, 2) mega(Params p) {
	.amdhsa_kernel _Z4megaILb1EEv6Params
		.amdhsa_group_segment_fixed_size 256
		.amdhsa_private_segment_fixed_size 0
		.amdhsa_kernarg_size 472
		.amdhsa_user_sgpr_count 2
		.amdhsa_user_sgpr_dispatch_ptr 0
		.amdhsa_user_sgpr_queue_ptr 0
		.amdhsa_user_sgpr_kernarg_segment_ptr 1
		.amdhsa_user_sgpr_dispatch_id 0
		.amdhsa_user_sgpr_kernarg_preload_length 0
		.amdhsa_user_sgpr_kernarg_preload_offset 0
		.amdhsa_user_sgpr_private_segment_size 0
		.amdhsa_uses_dynamic_stack 0
		.amdhsa_enable_private_segment 0
		.amdhsa_system_sgpr_workgroup_id_x 1
		.amdhsa_system_sgpr_workgroup_id_y 0
		.amdhsa_system_sgpr_workgroup_id_z 0
		.amdhsa_system_sgpr_workgroup_info 0
		.amdhsa_system_vgpr_workitem_id 2
		.amdhsa_next_free_vgpr 256
		.amdhsa_next_free_sgpr 100
		.amdhsa_accum_offset 256
		.amdhsa_reserve_vcc 1
		.amdhsa_float_round_mode_32 0
		.amdhsa_float_round_mode_16_64 0
		.amdhsa_float_denorm_mode_32 3
		.amdhsa_float_denorm_mode_16_64 3
		.amdhsa_dx10_clamp 1
		.amdhsa_ieee_mode 1
		.amdhsa_fp16_overflow 0
		.amdhsa_tg_split 0
		.amdhsa_exception_fp_ieee_invalid_op 0
		.amdhsa_exception_fp_denorm_src 0
		.amdhsa_exception_fp_ieee_div_zero 0
		.amdhsa_exception_fp_ieee_overflow 0
		.amdhsa_exception_fp_ieee_underflow 0
		.amdhsa_exception_fp_ieee_inexact 0
		.amdhsa_exception_int_div_zero 0
	.end_amdhsa_kernel

; template <bool COOP>
; __global__ void __launch_bounds__(NT, 2) mega(Params p) {
amdhsa.kernels:
  - .agpr_count:     0
    .args:
      - .offset:         0
        .size:           216
        .value_kind:     by_value
      - .offset:         216
        .size:           4
        .value_kind:     hidden_block_count_x
      - .offset:         220
        .size:           4
        .value_kind:     hidden_block_count_y
      - .offset:         224
        .size:           4
        .value_kind:     hidden_block_count_z
      - .offset:         228
        .size:           2
        .value_kind:     hidden_group_size_x
      - .offset:         230
        .size:           2
        .value_kind:     hidden_group_size_y
      - .offset:         232
        .size:           2
        .value_kind:     hidden_group_size_z
      - .offset:         234
        .size:           2
        .value_kind:     hidden_remainder_x
      - .offset:         236
        .size:           2
        .value_kind:     hidden_remainder_y
      - .offset:         238
        .size:           2
        .value_kind:     hidden_remainder_z
      - .offset:         256
        .size:           8
        .value_kind:     hidden_global_offset_x
      - .offset:         264
        .size:           8
        .value_kind:     hidden_global_offset_y
      - .offset:         272
        .size:           8
        .value_kind:     hidden_global_offset_z
      - .offset:         280
        .size:           2
        .value_kind:     hidden_grid_dims
      - .offset:         304
        .size:           8
        .value_kind:     hidden_multigrid_sync_arg
      - .offset:         336
        .size:           4
        .value_kind:     hidden_dynamic_lds_size
    .group_segment_fixed_size: 256
    .kernarg_segment_align: 8
    .kernarg_segment_size: 472
    .language:       OpenCL C
    .language_version:
      - 2
      - 0
    .max_flat_workgroup_size: 512
    .name:           _Z4megaILb1EEv6Params
    .private_segment_fixed_size: 0
    .sgpr_count:     106
    .sgpr_spill_count: 194
    .symbol:         _Z4megaILb1EEv6Params.kd
    .uniform_work_group_size: 1
    .uses_dynamic_stack: false
    .vgpr_count:     256
    .vgpr_spill_count: 0
    .wavefront_size: 64
